# LoRA GEMM: only the 128 K columns that are non-zero for a column block are multiplied (exact: the skipped weight blocks are zero)
# speedup vs baseline: 1.0240x; 1.0020x over previous
.LBB0_509:
	s_and_b64 vcc, exec, s[10:11]
	s_cbranch_vccz .LBB0_487
	s_lshl_b32 s26, s14, 8
	s_lshl_b64 s[30:31], s[26:27], 1
	s_ashr_i32 s12, s69, 31
	s_mul_i32 s12, s30, s12
	s_mul_hi_u32 s13, s30, s69
	s_add_i32 s12, s13, s12
	s_bfe_u32 s13, s14, 0x10017
	s_mul_i32 s15, s13, s69
	v_lshlrev_b32_e32 v0, 5, v0
	s_add_i32 s15, s12, s15
	s_ashr_i32 s12, s80, 31
	s_waitcnt vmcnt(7)
	v_and_b32_e32 v16, 32, v0
	v_lshlrev_b32_e32 v0, 6, v3
	s_mul_i32 s12, s30, s12
	s_mul_hi_u32 s21, s30, s80
	v_lshlrev_b32_e32 v5, 5, v5
	s_ashr_i32 s11, s87, 6
	v_sub_u32_e32 v0, v1, v0
	s_add_i32 s12, s21, s12
	s_mul_i32 s13, s13, s80
	v_and_b32_e32 v13, 32, v5
	v_lshlrev_b32_e32 v5, 6, v8
	s_ashr_i32 s10, s87, 8
	s_lshl_b32 s35, s11, 10
	v_ashrrev_i16_sdwa v0, v169, sext(v0) dst_sel:DWORD dst_unused:UNUSED_PAD src0_sel:DWORD src1_sel:BYTE_0
	s_add_i32 s13, s12, s13
	s_mul_i32 s12, s30, s80
	v_sub_u32_e32 v5, v6, v5
	v_bfe_i32 v17, v0, 0, 16
	s_add_u32 s12, s66, s12
	v_ashrrev_i16_sdwa v5, v169, sext(v5) dst_sel:DWORD dst_unused:UNUSED_PAD src0_sel:DWORD src1_sel:BYTE_0
	v_add_u32_e32 v0, v16, v17
	v_mul_lo_u32 v1, v4, s14
	s_addc_u32 s13, s67, s13
	s_cmp_eq_u32 s45, 3
	s_cbranch_scc0 .Llora_b0
	s_cmp_ge_i32 s80, 6
	s_cbranch_scc0 .Llora_b0
	s_add_u32 s12, s12, 0x100
	s_addc_u32 s13, s13, 0
.Llora_b0:
	s_add_i32 s81, s35, 0
	v_bfe_i32 v14, v5, 0, 16
	v_add_lshl_u32 v154, v1, v0, 1
	s_add_i32 m0, s81, 0x10000
	v_add_u32_e32 v5, v13, v14
	v_mul_lo_u32 v6, v9, s14
	s_mul_i32 s20, s30, s69
	global_load_lds_dwordx4 v154, s[12:13]
	s_add_i32 m0, s81, 0x12000
	v_add_lshl_u32 v146, v6, v5, 1
	v_mul_lo_u32 v18, v2, s14
	s_add_u32 s48, s92, s20
	v_mul_lo_u32 v15, v7, s14
	v_add_lshl_u32 v152, v0, v18, 1
	global_load_lds_dwordx4 v146, s[12:13]
	s_addc_u32 s49, s93, s15
	s_cmp_eq_u32 s45, 3
	s_cbranch_scc0 .Llora_a0
	s_cmp_ge_i32 s80, 6
	s_cbranch_scc0 .Llora_a0
	s_add_u32 s48, s48, 0x100
	s_addc_u32 s49, s49, 0
.Llora_a0:
	s_mov_b32 m0, s81
	s_add_i32 s21, s81, 0x2000
	v_add_lshl_u32 v144, v5, v15, 1
	global_load_lds_dwordx4 v152, s[48:49]
	s_mov_b32 m0, s21
	s_add_u32 s24, s12, s26
	global_load_lds_dwordx4 v144, s[48:49]
	s_addc_u32 s25, s13, 0
	s_add_i32 m0, s81, 0x14000
	v_mov_b32_e32 v155, v149
	global_load_lds_dwordx4 v154, s[24:25]
	s_add_i32 m0, s81, 0x16000
	s_add_u32 s36, s48, s26
	s_addc_u32 s37, s49, 0
	s_add_i32 s94, s81, 0x4000
	global_load_lds_dwordx4 v146, s[24:25]
	s_mov_b32 m0, s94
	s_add_i32 s22, s81, 0x6000
	global_load_lds_dwordx4 v152, s[36:37]
	s_mov_b32 m0, s22
	v_mov_b32_e32 v147, v149
	global_load_lds_dwordx4 v144, s[36:37]
	v_mov_b32_e32 v153, v149
	v_mov_b32_e32 v145, v149
	s_mov_b64 s[0:1], s[72:73]
	v_lshl_add_u64 v[10:11], s[12:13], 0, v[154:155]
	v_lshl_add_u64 v[8:9], s[12:13], 0, v[146:147]
	v_lshl_add_u64 v[6:7], s[48:49], 0, v[152:153]
	v_lshl_add_u64 v[4:5], s[48:49], 0, v[144:145]
	v_lshl_add_u64 v[2:3], s[24:25], 0, v[154:155]
	s_cmp_lg_u32 s10, 1
	v_lshl_add_u64 v[0:1], s[24:25], 0, v[146:147]
	s_cbranch_scc1 .LBB0_512
	s_barrier
.LBB0_512:
	s_and_b32 s23, s11, 3
	s_lshr_b32 s76, s14, 6
	s_cmp_eq_u32 s45, 3
	s_cselect_b32 s76, 2, s76
	s_lshl_b32 s11, s10, 13
	s_lshl_b32 s20, s23, 5
	s_lshl_b32 s15, s23, 12
	s_and_b64 s[6:7], exec, s[6:7]
	s_cselect_b32 s77, s59, s58
	s_add_i32 m0, s81, 0x18000
	v_lshl_add_u64 v[10:11], v[10:11], 0, s[52:53]
	s_waitcnt vmcnt(2)
	s_barrier
	global_load_lds_dwordx4 v[10:11], off
	v_lshl_add_u64 v[8:9], v[8:9], 0, s[52:53]
	s_add_i32 m0, s81, 0x1a000
	s_add_i32 s68, s81, 0x8000
	global_load_lds_dwordx4 v[8:9], off
	v_lshl_add_u64 v[6:7], v[6:7], 0, s[52:53]
	s_mov_b32 m0, s68
	s_add_i32 s14, s81, 0xa000
	global_load_lds_dwordx4 v[6:7], off
	v_lshl_add_u64 v[4:5], v[4:5], 0, s[52:53]
	s_mov_b32 m0, s14
	v_lshl_add_u64 v[2:3], v[2:3], 0, s[52:53]
	global_load_lds_dwordx4 v[4:5], off
	s_add_i32 m0, s81, 0x1c000
	v_lshl_add_u64 v[0:1], v[0:1], 0, s[52:53]
	global_load_lds_dwordx4 v[2:3], off
	s_add_i32 m0, s81, 0x1e000
	v_lshlrev_b32_e32 v2, 2, v12
	global_load_lds_dwordx4 v[0:1], off
	v_bfe_u32 v0, v12, 4, 2
	v_and_b32_e32 v1, 15, v12
	v_lshlrev_b32_e32 v148, 4, v0
	s_lshl_b32 s37, s2, 3
	v_lshl_or_b32 v151, s10, 6, v1
	v_lshl_or_b32 v1, v1, 6, v148
	v_and_b32_e32 v2, 32, v2
	s_abs_i32 s64, s37
	v_bitop3_b32 v3, v1, s11, v2 bitop3:0xde
	v_bitop3_b32 v185, s15, v1, v2 bitop3:0xf6
	v_cvt_f32_u32_e32 v1, s64
	v_lshl_add_u64 v[156:157], s[8:9], 0, v[148:149]
	v_cmp_eq_u32_e64 s[6:7], 0, v0
	v_lshl_or_b32 v186, v0, 3, s20
	v_rcp_iflag_f32_e32 v1, v1
	v_lshl_or_b32 v187, v0, 2, s20
	s_sub_i32 s8, 0, s64
	v_add_u32_e32 v0, v18, v16
	v_mul_f32_e32 v1, 0x4f7ffffe, v1
	v_cvt_u32_f32_e32 v1, v1
	s_waitcnt vmcnt(6)
	v_add_lshl_u32 v148, v0, v17, 1
	v_add_u32_e32 v0, v15, v13
	v_readfirstlane_b32 s9, v1
	s_mul_i32 s8, s8, s9
	s_mul_hi_u32 s8, s9, s8
	v_lshl_add_u64 v[158:159], s[26:27], 0, v[148:149]
	v_add_lshl_u32 v148, v0, v14, 1
	s_add_i32 s15, s76, -2
	s_mov_b32 s83, s82
	s_mov_b32 s90, s82
	s_mov_b32 s91, s82
	s_mov_b32 s36, 0
	s_ashr_i32 s46, s77, 31
	s_ashr_i32 s73, s34, 31
	s_mov_b32 s43, s27
	s_lshr_b32 s97, s42, 3
	s_bfe_i32 s2, s2, 0x1001c
	s_add_i32 s24, s9, s8
	v_lshl_add_u64 v[160:161], s[26:27], 0, v[148:149]
	v_add_u32_e32 v188, 0, v3
	s_barrier
	s_branch .LBB0_515

.LBB0_521:
	s_cmp_eq_u32 s45, 3
	s_cbranch_scc0 .Llora_n
	s_cmp_ge_i32 s80, 6
	s_cbranch_scc0 .Llora_n
	s_cmp_lg_u64 s[8:9], 0
	s_cbranch_scc1 .Llora_n
	s_add_u32 s48, s48, 0x100
	s_addc_u32 s49, s49, 0
	s_add_u32 s12, s12, 0x100
	s_addc_u32 s13, s13, 0
